# v015 + dif-attention: map-0 PV LDS reads pipelined, next-tile loads at tile top, skew sleep 5->1
# speedup vs baseline: 1.0048x; 1.0048x over previous
; #define LAS __attribute__((address_space(3)))
; __device__ __forceinline__ void attn_dif_unit(LAS unsigned char* lds, const int tid, const int wave_s, const bf16_t* q, const bf16_t* k0, const bf16_t* k1, const bf16_t* vt0, const bf16_t* vt1, ...
;     ...
;     DA_LOAD(0);
; #pragma unroll 1
;     for (int t = 0; t < ntile; ++t) {
;         LAS unsigned char* kb = lds + (t & 1) * DA_BUF; LAS unsigned char* vb = kb + DA_KT;
; #pragma unroll
;         for (int i = 0; i < 2; ++i) { *(LAS u32x4*)(kb + srow * DA_KP + (sch + 8 * i) * 16) = kreg[i];
;             LAS unsigned char* p = vb + (srow + 64 * i) * DA_VP + (sch >> 1) * 32 + (sch & 1) * 8; *(LAS u32x2*)p = (u32x2){vreg[i].x, vreg[i].y}; *(LAS u32x2*)(p + 16) = (u32x2){vreg[i].z, vreg[i].w}; }
;         asm volatile("s_waitcnt lgkmcnt(0)" ::: "memory"); __builtin_amdgcn_s_barrier(); asm volatile("" ::: "memory");
;         if (wave_s >= 4) __builtin_amdgcn_s_sleep(DA_SKEW);
.LBB0_987:
	s_bitcmp1_b32 s55, 0
	s_cselect_b32 s6, 0, 0x8c00
	s_add_i32 s22, s6, 0
	v_add_u32_e32 v2, s22, v211
	v_add3_u32 v2, v2, v212, v214
	v_add3_u32 v0, s22, v210, v209
	v_add_u32_e32 v3, 0x4000, v2
	s_waitcnt vmcnt(3)
	ds_write_b128 v0, v[176:179]
	s_waitcnt vmcnt(1)
	ds_write2_b64 v3, v[184:185], v[186:187] offset0:128 offset1:130
	s_waitcnt vmcnt(1)
	ds_write_b128 v0, v[180:183] offset:128
	v_add_u32_e32 v0, 0x6800, v2
	s_waitcnt vmcnt(0)
	ds_write2_b64 v0, v[188:189], v[190:191] offset1:2
	s_waitcnt lgkmcnt(0)
	s_barrier
	s_cmp_ge_u32 s55, s49
	s_cbranch_scc1 .Ldif_noload
	s_lshl_b64 s[6:7], s[24:25], 12
	s_add_u32 s10, s43, s6
	s_addc_u32 s11, s46, s7
	s_lshl_b64 s[6:7], s[24:25], 1
	s_add_u32 s12, s47, s6
	s_addc_u32 s13, s48, s7
	s_cmp_lt_u32 s55, s41
	s_cselect_b32 s7, s54, s11
	s_cselect_b32 s6, s53, s10
	v_lshl_add_u64 v[180:181], s[6:7], 0, v[198:199]
	s_cselect_b32 s7, s52, s13
	s_cselect_b32 s6, s51, s12
	v_lshl_add_u64 v[184:185], s[6:7], 0, v[200:201]
	v_add_co_u32_e32 v188, vcc, 0x48000, v184
	global_load_dwordx4 v[176:179], v[180:181], off
	s_nop 0
	global_load_dwordx4 v[180:183], v[180:181], off offset:128
	v_addc_co_u32_e32 v189, vcc, 0, v185, vcc
	global_load_dwordx4 v[184:187], v[184:185], off
	s_nop 0
	global_load_dwordx4 v[188:191], v[188:189], off
.Ldif_noload:
	s_andn2_b64 vcc, exec, s[80:81]
	s_cbranch_vccnz .LBB0_989
	s_sleep 1

; __device__ __forceinline__ void attn_dif_unit(LAS unsigned char* lds, const int tid, const int wave_s, const bf16_t* q, const bf16_t* k0, const bf16_t* k1, const bf16_t* vt0, const bf16_t* vt1, ...
;     ...
;             f32x16 sacc[2]; const float nm = -m_used[m];
;             {
;                 bf16x8 qf[4], kfa[4], kfb[4];
; #pragma unroll
;                 for (int ks = 0; ks < 4; ++ks) qf[ks] = *(const LAS bf16x8*)(qb + c32 * DA_KP + m * 128 + ks * 32 + hi * 16);
; #pragma unroll
;                 for (int ks = 0; ks < 4; ++ks) kfa[ks] = *(const LAS bf16x8*)(kb + c32 * DA_KP + m * 128 + ks * 32 + hi * 16);
; #pragma unroll
;                 for (int ks = 0; ks < 4; ++ks) kfb[ks] = *(const LAS bf16x8*)(kb + (32 + c32) * DA_KP + m * 128 + ks * 32 + hi * 16);
; #pragma unroll
;                 for (int r = 0; r < 16; ++r) { sacc[0][r] = nm; sacc[1][r] = nm; }
; #pragma unroll
;                 for (int ks = 0; ks < 4; ++ks) sacc[0] = __builtin_amdgcn_mfma_f32_32x32x16_bf16(kfa[ks], qf[ks], sacc[0], 0, 0, 0);
; #pragma unroll
;                 for (int ks = 0; ks < 4; ++ks) sacc[1] = __builtin_amdgcn_mfma_f32_32x32x16_bf16(kfb[ks], qf[ks], sacc[1], 0, 0, 0);
;             }
;             float mx = fmaxf(sacc[0][0], sacc[1][0]);
; #pragma unroll
;             for (int a = 0; a < 2; ++a)
; #pragma unroll
;     ...
;             float ls = 0.f;
; #pragma unroll
;             for (int a = 0; a < 2; ++a)
; #pragma unroll
;                 for (int r = 0; r < 16; ++r) { const float p = ex2(sacc[a][r]); sacc[a][r] = p; ls += p; }
;             l_run[m] += ls;
;             bf16x8 pf[4];
; #pragma unroll
;             for (int a = 0; a < 2; ++a)
; #pragma unroll
;                 for (int jj = 0; jj < 2; ++jj) { u32x4 wv; wv.x = cvt_pk_bf16(sacc[a][8 * jj + 0], sacc[a][8 * jj + 1]); wv.y = cvt_pk_bf16(sacc[a][8 * jj + 2], sacc[a][8 * jj + 3]);
;                     wv.z = cvt_pk_bf16(sacc[a][8 * jj + 4], sacc[a][8 * jj + 5]); wv.w = cvt_pk_bf16(sacc[a][8 * jj + 6], sacc[a][8 * jj + 7]); pf[2 * a + jj] = __builtin_bit_cast(bf16x8, wv); }
;             if (m == 1 && t + 1 < ntile) DA_LOAD(t + 1);
;             {
;                 const LAS unsigned char* vp0 = vb + c32 * DA_VP + hi * 16;
;     ...
;                 bf16x8 va[4], vc[4];
;                 DA_VF(va, 0); DA_VF(vc, 1); DA_PV(va, 0); DA_VF(va, 2); DA_PV(vc, 1); DA_VF(vc, 3); DA_PV(va, 2); DA_PV(vc, 3);
.LBB0_997:
	v_mul_u32_u24_e32 v0, 0x90, v208
	v_add_u32_e32 v0, s22, v0
	v_add_u32_e32 v220, v0, v213
	v_exp_f32_e32 v221, v160
	v_exp_f32_e32 v222, v14
	v_exp_f32_e32 v223, v15
	v_exp_f32_e32 v224, v12
	v_exp_f32_e32 v225, v13
	v_exp_f32_e32 v226, v10
	v_exp_f32_e32 v227, v11
	v_exp_f32_e32 v228, v8
	v_exp_f32_e32 v229, v9
	v_exp_f32_e32 v230, v6
	v_exp_f32_e32 v231, v7
	v_exp_f32_e32 v232, v4
	v_exp_f32_e32 v233, v5
	v_exp_f32_e32 v234, v2
	v_exp_f32_e32 v235, v3
	v_exp_f32_e32 v236, v175
	v_exp_f32_e32 v237, v144
	v_exp_f32_e32 v238, v145
	v_exp_f32_e32 v239, v146
	v_exp_f32_e32 v247, v147
	v_exp_f32_e32 v241, v148
	v_exp_f32_e32 v243, v149
	v_exp_f32_e32 v240, v150
	v_exp_f32_e32 v192, v151
	v_exp_f32_e32 v193, v152
	v_exp_f32_e32 v194, v153
	v_exp_f32_e32 v195, v154
	v_exp_f32_e32 v196, v155
	v_exp_f32_e32 v197, v156
	v_exp_f32_e32 v242, v157
	v_exp_f32_e32 v250, v158
	v_exp_f32_e32 v251, v159
	ds_read_b128 v[148:151], v220 offset:17408
	ds_read_b128 v[152:155], v220 offset:17440
	ds_read_b128 v[156:159], v220 offset:17472
	ds_read_b128 v[160:163], v220 offset:17504
	ds_read_b128 v[164:167], v220 offset:22016
	ds_read_b128 v[168:171], v220 offset:22048
	v_cvt_pk_bf16_f32 v2, v221, v222
	v_cvt_pk_bf16_f32 v3, v223, v224
	v_cvt_pk_bf16_f32 v4, v225, v226
	v_cvt_pk_bf16_f32 v5, v227, v228
	v_cvt_pk_bf16_f32 v6, v229, v230
	v_cvt_pk_bf16_f32 v7, v231, v232
	v_cvt_pk_bf16_f32 v8, v233, v234
	v_cvt_pk_bf16_f32 v9, v235, v236
	v_cvt_pk_bf16_f32 v10, v237, v238
	v_cvt_pk_bf16_f32 v11, v239, v247
	v_cvt_pk_bf16_f32 v12, v241, v243
	v_cvt_pk_bf16_f32 v13, v240, v192
	v_cvt_pk_bf16_f32 v144, v193, v194
	v_cvt_pk_bf16_f32 v145, v195, v196
	v_cvt_pk_bf16_f32 v146, v197, v242
	v_cvt_pk_bf16_f32 v147, v250, v251
	s_waitcnt lgkmcnt(5)
	v_mfma_f32_32x32x16_bf16 v[128:143], v[148:151], v[2:5], v[128:143]
	ds_read_b128 v[172:175], v220 offset:22080
	s_waitcnt lgkmcnt(5)
	v_mfma_f32_32x32x16_bf16 v[128:143], v[152:155], v[6:9], v[128:143]
	ds_read_b128 v[148:151], v220 offset:22112
	s_waitcnt lgkmcnt(5)
	v_mfma_f32_32x32x16_bf16 v[128:143], v[156:159], v[10:13], v[128:143]
	ds_read_b128 v[152:155], v220 offset:26624
	s_waitcnt lgkmcnt(5)
	v_mfma_f32_32x32x16_bf16 v[128:143], v[160:163], v[144:147], v[128:143]
	ds_read_b128 v[156:159], v220 offset:26656
	s_waitcnt lgkmcnt(5)
	v_mfma_f32_32x32x16_bf16 v[96:111], v[164:167], v[2:5], v[96:111]
	ds_read_b128 v[160:163], v220 offset:26688
	s_waitcnt lgkmcnt(5)
	v_mfma_f32_32x32x16_bf16 v[96:111], v[168:171], v[6:9], v[96:111]
	ds_read_b128 v[164:167], v220 offset:26720
	s_waitcnt lgkmcnt(5)
	v_mfma_f32_32x32x16_bf16 v[96:111], v[172:175], v[10:13], v[96:111]
	ds_read_b128 v[168:171], v220 offset:31232
	s_waitcnt lgkmcnt(5)
	v_mfma_f32_32x32x16_bf16 v[96:111], v[148:151], v[144:147], v[96:111]
	ds_read_b128 v[172:175], v220 offset:31264
	s_waitcnt lgkmcnt(5)
	v_mfma_f32_32x32x16_bf16 v[64:79], v[152:155], v[2:5], v[64:79]
	ds_read_b128 v[148:151], v220 offset:31296
	s_waitcnt lgkmcnt(5)
	v_mfma_f32_32x32x16_bf16 v[64:79], v[156:159], v[6:9], v[64:79]
	ds_read_b128 v[152:155], v220 offset:31328
	s_waitcnt lgkmcnt(5)
	v_mfma_f32_32x32x16_bf16 v[64:79], v[160:163], v[10:13], v[64:79]
	s_waitcnt lgkmcnt(4)
	v_mfma_f32_32x32x16_bf16 v[64:79], v[164:167], v[144:147], v[64:79]
	s_waitcnt lgkmcnt(3)
	v_mfma_f32_32x32x16_bf16 v[32:47], v[168:171], v[2:5], v[32:47]
	s_waitcnt lgkmcnt(2)
	v_mfma_f32_32x32x16_bf16 v[32:47], v[172:175], v[6:9], v[32:47]
	s_waitcnt lgkmcnt(1)
	v_mfma_f32_32x32x16_bf16 v[32:47], v[148:151], v[10:13], v[32:47]
	s_waitcnt lgkmcnt(0)
	v_mfma_f32_32x32x16_bf16 v[32:47], v[152:155], v[144:147], v[32:47]
	ds_read_b128 v[2:5], v215 offset:128
	ds_read_b128 v[6:9], v252 offset:128
	v_xor_b32_e32 v144, 0x80000000, v217
	v_mov_b32_e32 v145, v144
	v_mov_b32_e32 v146, v144
	v_mov_b32_e32 v147, v144
	v_mov_b32_e32 v148, v144
	v_mov_b32_e32 v149, v144
	v_mov_b32_e32 v150, v144
	v_mov_b32_e32 v151, v144
	v_mov_b32_e32 v152, v144
	v_mov_b32_e32 v153, v144
	v_mov_b32_e32 v154, v144
	v_mov_b32_e32 v155, v144
	v_mov_b32_e32 v156, v144
	v_mov_b32_e32 v157, v144
	v_mov_b32_e32 v158, v144
	v_mov_b32_e32 v159, v144
	s_and_b64 vcc, exec, s[10:11]
	s_waitcnt lgkmcnt(0)
	v_mfma_f32_32x32x16_bf16 v[160:175], v[6:9], v[2:5], v[144:159]
	ds_read_b128 v[6:9], v252 offset:160
	ds_read_b128 v[10:13], v215 offset:160
	s_waitcnt lgkmcnt(0)
	v_mfma_f32_32x32x16_bf16 v[160:175], v[6:9], v[10:13], v[160:175]
	ds_read_b128 v[6:9], v252 offset:192
	ds_read_b128 v[204:207], v215 offset:192
	s_waitcnt lgkmcnt(0)
	v_mfma_f32_32x32x16_bf16 v[160:175], v[6:9], v[204:207], v[160:175]
	ds_read_b128 v[6:9], v252 offset:8832
	s_waitcnt lgkmcnt(0)
	v_mfma_f32_32x32x16_bf16 v[144:159], v[6:9], v[2:5], v[144:159]
	ds_read_b128 v[2:5], v252 offset:8864
	s_waitcnt lgkmcnt(0)
	v_mfma_f32_32x32x16_bf16 v[144:159], v[2:5], v[10:13], v[144:159]
	ds_read_b128 v[2:5], v252 offset:8896
	s_waitcnt lgkmcnt(0)
	v_mfma_f32_32x32x16_bf16 v[144:159], v[2:5], v[204:207], v[144:159]
	ds_read_b128 v[2:5], v252 offset:8928
	ds_read_b128 v[6:9], v215 offset:224
	s_waitcnt lgkmcnt(0)
	v_mfma_f32_32x32x16_bf16 v[144:159], v[2:5], v[6:9], v[144:159]
	ds_read_b128 v[2:5], v252 offset:224
	s_waitcnt lgkmcnt(0)
	v_mfma_f32_32x32x16_bf16 v[160:175], v[2:5], v[6:9], v[160:175]
	s_nop 8
	v_max_f32_e32 v0, v144, v144
	s_nop 1
	v_max_f32_e32 v2, v160, v160
	v_max_f32_e32 v0, v2, v0
	v_max3_f32 v0, v0, v161, v162
	v_max3_f32 v0, v0, v163, v164
	v_max3_f32 v0, v0, v165, v166
	v_max3_f32 v0, v0, v167, v168
	v_max3_f32 v0, v0, v169, v170
	v_max3_f32 v0, v0, v171, v172
	v_max3_f32 v0, v0, v173, v174
	v_max3_f32 v0, v0, v175, v145
	v_max3_f32 v0, v0, v146, v147
	v_max3_f32 v0, v0, v148, v149
	v_max3_f32 v0, v0, v150, v151
	v_max3_f32 v0, v0, v152, v153
	v_max3_f32 v0, v0, v154, v155
	v_max3_f32 v0, v0, v156, v157
	v_max3_f32 v0, v0, v158, v159
	ds_bpermute_b32 v2, v203, v0
	s_waitcnt lgkmcnt(0)
	v_max_f32_e32 v2, v2, v2
	v_max_f32_e32 v252, v0, v2
	s_cbranch_vccz .LBB0_1001
	v_cmp_lt_f32_e32 vcc, s64, v252
	s_mov_b64 s[12:13], 0
	s_mov_b64 s[10:11], 0
	s_cbranch_vccz .LBB0_1000
	v_max_f32_e32 v0, v252, v252
	v_max_f32_e32 v0, 0, v0
	s_mov_b64 s[10:11], -1

; __device__ __forceinline__ unsigned cvt_pk_bf16(float lo, float hi) { unsigned r; asm volatile("v_cvt_pk_bf16_f32 %0, %1, %2" : "=v"(r) : "v"(lo), "v"(hi)); return r; }
; __device__ __forceinline__ float ex2(float x) { return __builtin_amdgcn_exp2f(x); }
; __device__ __forceinline__ void attn_dif_unit(LAS unsigned char* lds, const int tid, const int wave_s, const bf16_t* q, const bf16_t* k0, const bf16_t* k1, const bf16_t* vt0, const bf16_t* vt1, ...
;     ...
;             float ls = 0.f;
; #pragma unroll
;             for (int a = 0; a < 2; ++a)
; #pragma unroll
;                 for (int r = 0; r < 16; ++r) { const float p = ex2(sacc[a][r]); sacc[a][r] = p; ls += p; }
;             l_run[m] += ls;
;             bf16x8 pf[4];
; #pragma unroll
;             for (int a = 0; a < 2; ++a)
; #pragma unroll
;                 for (int jj = 0; jj < 2; ++jj) { u32x4 wv; wv.x = cvt_pk_bf16(sacc[a][8 * jj + 0], sacc[a][8 * jj + 1]); wv.y = cvt_pk_bf16(sacc[a][8 * jj + 2], sacc[a][8 * jj + 3]);
;                     wv.z = cvt_pk_bf16(sacc[a][8 * jj + 4], sacc[a][8 * jj + 5]); wv.w = cvt_pk_bf16(sacc[a][8 * jj + 6], sacc[a][8 * jj + 7]); pf[2 * a + jj] = __builtin_bit_cast(bf16x8, wv); }
;             if (m == 1 && t + 1 < ntile) DA_LOAD(t + 1);
.LBB0_1005:
	v_exp_f32_e32 v0, v160
	v_exp_f32_e32 v14, v14
	v_exp_f32_e32 v15, v15
	v_exp_f32_e32 v160, v12
	v_exp_f32_e32 v161, v13
	v_exp_f32_e32 v162, v10
	v_exp_f32_e32 v163, v11
	v_exp_f32_e32 v164, v8
	v_exp_f32_e32 v165, v9
	v_exp_f32_e32 v166, v6
	v_exp_f32_e32 v167, v7
	v_exp_f32_e32 v168, v4
	v_exp_f32_e32 v169, v5
	v_exp_f32_e32 v170, v2
	v_exp_f32_e32 v171, v3
	v_exp_f32_e32 v172, v175
	v_exp_f32_e32 v173, v144
	v_exp_f32_e32 v174, v145
	v_exp_f32_e32 v175, v146
	v_exp_f32_e32 v252, v147
	v_exp_f32_e32 v148, v148
	v_exp_f32_e32 v149, v149
	v_exp_f32_e32 v150, v150
	v_exp_f32_e32 v151, v151
	v_exp_f32_e32 v152, v152
	v_exp_f32_e32 v153, v153
	v_exp_f32_e32 v154, v154
	v_exp_f32_e32 v155, v155
	v_exp_f32_e32 v156, v156
	v_exp_f32_e32 v157, v157
	v_exp_f32_e32 v158, v158
	v_exp_f32_e32 v159, v159
	s_cmp_ge_u32 s55, s49
	v_cvt_pk_bf16_f32 v144, v0, v14
	v_cvt_pk_bf16_f32 v145, v15, v160
	v_cvt_pk_bf16_f32 v146, v161, v162
	v_cvt_pk_bf16_f32 v147, v163, v164
	v_cvt_pk_bf16_f32 v10, v165, v166
	v_cvt_pk_bf16_f32 v11, v167, v168
	v_cvt_pk_bf16_f32 v12, v169, v170
	v_cvt_pk_bf16_f32 v13, v171, v172
	v_cvt_pk_bf16_f32 v6, v173, v174
	v_cvt_pk_bf16_f32 v7, v175, v252
	v_cvt_pk_bf16_f32 v8, v148, v149
	v_cvt_pk_bf16_f32 v9, v150, v151
	v_cvt_pk_bf16_f32 v2, v152, v153
	v_cvt_pk_bf16_f32 v3, v154, v155
	v_cvt_pk_bf16_f32 v4, v156, v157
	v_cvt_pk_bf16_f32 v5, v158, v159
	s_branch .LBB0_986
